# MLA unit prologue: rotary-table entries loaded together up front, top-of-unit vmcnt drain removed
# baseline (speedup 1.0000x reference)
; __device__ __forceinline__ float bf2f(unsigned short h) { return __uint_as_float(((unsigned)h) << 16); }
; __device__ __forceinline__ void rope_cs(int pos, int idx64, float& cs, float& sn) {
;     const double rev = (double)pos * ROPE_REV[idx64];
;     const float fr = (float)(rev - __builtin_rint(rev));
;     cs = __builtin_amdgcn_cosf(fr); sn = __builtin_amdgcn_sinf(fr);
; template <int DQK, int DV, int MODE, int QPRE, bool DIFF> ...
;     ...
;     { const bf16_t* qrow = Q + mp * 256 + (size_t)(q0 + wid * 32 + l32) * ldq + hi * 8;
; #pragma unroll
;       for (int d0 = 0; d0 < ND0; ++d0) qf[d0] = *(const bf16x8*)(qrow + d0 * 16); }
;     if (QPRE != 0) {
;         float v[ND0][8]; float s = 0.f;
; #pragma unroll
;         for (int d0 = 0; d0 < ND0; ++d0)
; #pragma unroll
;             for (int j = 0; j < 8; ++j) { v[d0][j] = bf2f((unsigned short)qf[d0][j]); s += v[d0][j] * v[d0][j]; }
;         { float a, b; swap32(s, a, b); s = a + b; }
;         const float rs = 1.0f / sqrtf(s * (1.0f / DQK) + EPS);
; #pragma unroll
;         for (int d0 = 0; d0 < ND0; ++d0) { const f32x4 g0 = *(const f32x4*)(qg + d0 * 16 + hi * 8), g1 = *(const f32x4*)(qg + d0 * 16 + hi * 8 + 4);
; #pragma unroll
;             for (int j = 0; j < 4; ++j) { v[d0][j] *= rs * c * g0[j]; v[d0][4 + j] *= rs * c * g1[j]; } }
;         if (QPRE == 3) {
;             const int pos = q0 + wid * 32 + l32;
; #pragma unroll
;             for (int j = 0; j < 8; ++j) { float cs, sn; rope_cs(pos, 2 * (8 * hi + j), cs, sn); const float x1 = v[ND0 - 2][j], x2 = v[ND0 - 1][j];
.LBB0_1637:
	s_ashr_i32 s4, s2, 7
	s_sub_i32 s27, 15, s4
	s_lshl_b32 s4, s2, 8
	s_and_b32 s52, s4, 0x7000
	s_and_b32 s53, s2, 15
	s_mul_i32 s6, s52, 0xc00
	s_add_u32 s4, s0, s6
	s_addc_u32 s5, s1, 0
	s_mul_i32 s26, s53, 0xc0
	s_add_u32 s4, s4, s26
	s_addc_u32 s5, s5, 0
	s_add_u32 s6, s3, s6
	s_addc_u32 s7, s28, 0
	v_mbcnt_lo_u32_b32 v167, -1, 0
	v_mbcnt_hi_u32_b32 v167, -1, v167
	s_add_u32 s10, s6, s26
	v_ashrrev_i32_e32 v182, 5, v167
	v_lshlrev_b32_e32 v170, 4, v182
	s_addc_u32 s11, s7, 0
	v_ashrrev_i32_e32 v171, 31, v170
	v_lshlrev_b64 v[82:83], 3, v[170:171]
	s_getpc_b64 s[6:7]
	s_add_u32 s6, s6, _ZL8ROPE_REV@rel32@lo+4
	s_addc_u32 s7, s7, _ZL8ROPE_REV@rel32@hi+12
	s_waitcnt lgkmcnt(0)
	v_lshl_add_u64 v[0:1], s[6:7], 0, v[82:83]
	global_load_dwordx2 v[204:205], v[0:1], off
	global_load_dwordx2 v[206:207], v[0:1], off offset:16
	global_load_dwordx2 v[208:209], v[0:1], off offset:32
	global_load_dwordx2 v[210:211], v[0:1], off offset:48
	global_load_dwordx2 v[212:213], v[0:1], off offset:64
	global_load_dwordx2 v[214:215], v[0:1], off offset:80
	global_load_dwordx2 v[216:217], v[0:1], off offset:96
	global_load_dwordx2 v[218:219], v[0:1], off offset:112
	s_lshl_b32 s56, s27, 8
	v_mov_b64_e32 v[50:51], s[4:5]
	s_getpc_b64 s[4:5]
	s_add_u32 s4, s4, _ZL8ROPE_REV@rel32@lo+20
	s_addc_u32 s5, s5, _ZL8ROPE_REV@rel32@hi+28
	v_and_b32_e32 v166, 31, v167
	s_add_i32 s56, s56, s36
	v_or_b32_e32 v168, s56, v166
	v_cvt_f64_u32_e32 v[80:81], v168
	v_lshlrev_b32_e32 v48, 3, v182
	v_ashrrev_i32_e32 v49, 31, v48
	v_lshl_add_u64 v[76:77], s[4:5], 0, v[82:83]
	v_mad_u64_u32 v[50:51], s[4:5], v168, s39, v[50:51]
	v_lshl_add_u64 v[4:5], v[48:49], 2, s[16:17]
	v_lshl_add_u64 v[64:65], v[48:49], 1, v[50:51]
	global_load_dwordx4 v[40:43], v[4:5], off offset:16
	global_load_dwordx4 v[44:47], v[4:5], off
	global_load_dwordx4 v[32:35], v[4:5], off offset:80
	global_load_dwordx4 v[36:39], v[4:5], off offset:64
	global_load_dwordx4 v[24:27], v[4:5], off offset:144
	global_load_dwordx4 v[28:31], v[4:5], off offset:128
	global_load_dwordx4 v[16:19], v[4:5], off offset:208
	global_load_dwordx4 v[20:23], v[4:5], off offset:192
	global_load_dwordx4 v[8:11], v[4:5], off offset:272
	global_load_dwordx4 v[12:15], v[4:5], off offset:256
	global_load_dwordx4 v[0:3], v[4:5], off offset:336
	s_nop 0
	global_load_dwordx4 v[4:7], v[4:5], off offset:320
	s_nop 0
	global_load_dwordx4 v[48:51], v[64:65], off
	global_load_dwordx4 v[52:55], v[64:65], off offset:32
	s_getpc_b64 s[4:5]
	s_add_u32 s4, s4, _ZL8ROPE_REV@rel32@lo+36
	s_addc_u32 s5, s5, _ZL8ROPE_REV@rel32@hi+44
	v_add_u32_e32 v172, s35, v167
	v_cmp_gt_i32_e64 s[6:7], s42, v172
	s_waitcnt vmcnt(0)
	v_mul_f64 v[58:59], v[204:205], v[80:81]
	v_rndne_f64_e32 v[58:59], v[58:59]
	v_fma_f64 v[56:57], v[204:205], v[80:81], -v[58:59]
	v_cvt_f32_f64_e32 v56, v[56:57]
	v_cos_f32_e32 v74, v56
	v_sin_f32_e32 v72, v56
	global_load_dwordx4 v[56:59], v[64:65], off offset:64
	global_load_dwordx4 v[60:63], v[64:65], off offset:96
	global_load_dwordx4 v[68:71], v[64:65], off offset:128
	s_nop 0
	global_load_dwordx4 v[64:67], v[64:65], off offset:160
	v_and_b32_e32 v163, 0xffff0000, v48
	v_and_b32_e32 v151, 0xffff0000, v55
	v_lshlrev_b32_e32 v150, 16, v55
	v_and_b32_e32 v157, 0xffff0000, v54
	v_lshlrev_b32_e32 v156, 16, v54
	v_lshlrev_b32_e32 v162, 16, v48
	v_mul_f32_e32 v48, v163, v163
	v_and_b32_e32 v159, 0xffff0000, v51
	v_lshlrev_b32_e32 v158, 16, v51
	v_and_b32_e32 v161, 0xffff0000, v50
	v_lshlrev_b32_e32 v160, 16, v50
	v_and_b32_e32 v51, 0xffff0000, v49
	v_lshlrev_b32_e32 v50, 16, v49
	v_pk_fma_f32 v[48:49], v[162:163], v[162:163], v[48:49] op_sel_hi:[1,1,0]
	v_mul_f32_e32 v88, v159, v159
	v_pk_fma_f32 v[48:49], v[50:51], v[50:51], v[48:49]
	v_and_b32_e32 v155, 0xffff0000, v53
	v_lshlrev_b32_e32 v154, 16, v53
	v_and_b32_e32 v53, 0xffff0000, v52
	v_lshlrev_b32_e32 v52, 16, v52
	v_mul_f32_e32 v90, v53, v53
	v_mul_f32_e32 v92, v155, v155
	v_mul_f32_e32 v94, v157, v157
	v_mul_f32_e32 v96, v151, v151
	s_waitcnt vmcnt(3)
	v_and_b32_e32 v149, 0xffff0000, v56
	v_lshlrev_b32_e32 v148, 16, v56
	v_mul_f32_e32 v98, v149, v149
	v_and_b32_e32 v145, 0xffff0000, v59
	v_lshlrev_b32_e32 v144, 16, v59
	s_waitcnt vmcnt(0)
	v_mul_f64 v[78:79], v[206:207], v[80:81]
	v_rndne_f64_e32 v[78:79], v[78:79]
	v_fma_f64 v[76:77], v[206:207], v[80:81], -v[78:79]
	v_cvt_f32_f64_e32 v73, v[76:77]
	v_cos_f32_e32 v75, v73
	v_sin_f32_e32 v73, v73
	v_lshl_add_u64 v[76:77], s[4:5], 0, v[82:83]
	s_getpc_b64 s[4:5]
	s_add_u32 s4, s4, _ZL8ROPE_REV@rel32@lo+52
	s_addc_u32 s5, s5, _ZL8ROPE_REV@rel32@hi+60
	v_lshl_add_u64 v[84:85], s[4:5], 0, v[82:83]
	s_getpc_b64 s[4:5]
	s_add_u32 s4, s4, _ZL8ROPE_REV@rel32@lo+68
	s_addc_u32 s5, s5, _ZL8ROPE_REV@rel32@hi+76
	v_and_b32_e32 v147, 0xffff0000, v58
	v_lshlrev_b32_e32 v146, 16, v58
	v_and_b32_e32 v59, 0xffff0000, v57
	v_lshlrev_b32_e32 v58, 16, v57
	v_mul_f32_e32 v100, v59, v59
	v_mul_f32_e32 v102, v147, v147
	v_mul_f32_e32 v104, v145, v145
	v_and_b32_e32 v141, 0xffff0000, v63
	v_lshlrev_b32_e32 v140, 16, v63
	v_and_b32_e32 v143, 0xffff0000, v62
	v_lshlrev_b32_e32 v142, 16, v62
	v_and_b32_e32 v63, 0xffff0000, v61
	v_lshlrev_b32_e32 v62, 16, v61
	v_and_b32_e32 v61, 0xffff0000, v60
	v_lshlrev_b32_e32 v60, 16, v60
	v_mul_f32_e32 v106, v61, v61
	v_mul_f32_e32 v108, v63, v63
	v_mul_f32_e32 v110, v143, v143
	v_mul_f32_e32 v112, v141, v141
	v_and_b32_e32 v139, 0xffff0000, v69
	v_lshlrev_b32_e32 v138, 16, v69
	v_and_b32_e32 v69, 0xffff0000, v68
	v_lshlrev_b32_e32 v68, 16, v68
	v_mul_f32_e32 v114, v69, v69
	v_mul_f32_e32 v116, v139, v139
	v_and_b32_e32 v137, 0xffff0000, v70
	v_lshlrev_b32_e32 v136, 16, v70
	v_mul_f32_e32 v118, v137, v137
	v_and_b32_e32 v135, 0xffff0000, v71
	v_lshlrev_b32_e32 v134, 16, v71
	v_mul_f32_e32 v120, v135, v135
	v_and_b32_e32 v71, 0xffff0000, v65
	v_lshlrev_b32_e32 v70, 16, v65
	v_and_b32_e32 v65, 0xffff0000, v64
	v_lshlrev_b32_e32 v64, 16, v64
	v_mul_f32_e32 v122, v65, v65
	v_mul_f32_e32 v124, v71, v71
	v_and_b32_e32 v133, 0xffff0000, v67
	v_lshlrev_b32_e32 v132, 16, v67
	v_and_b32_e32 v67, 0xffff0000, v66
	v_lshlrev_b32_e32 v66, 16, v66
	v_mul_f32_e32 v126, v67, v67
	v_mul_f32_e32 v164, v133, v133
	s_waitcnt vmcnt(0)
; __device__ __forceinline__ float bf2f(unsigned short h) { return __uint_as_float(((unsigned)h) << 16); }
; template <int DQK, int DV, int MODE, int QPRE, bool DIFF> ...
;     ...
;         float v[ND0][8]; float s = 0.f;
; #pragma unroll
;         for (int d0 = 0; d0 < ND0; ++d0)
; #pragma unroll
;             for (int j = 0; j < 8; ++j) { v[d0][j] = bf2f((unsigned short)qf[d0][j]); s += v[d0][j] * v[d0][j]; }
;         { float a, b; swap32(s, a, b); s = a + b; }
;         const float rs = 1.0f / sqrtf(s * (1.0f / DQK) + EPS);
; #pragma unroll
;         for (int d0 = 0; d0 < ND0; ++d0) { const f32x4 g0 = *(const f32x4*)(qg + d0 * 16 + hi * 8), g1 = *(const f32x4*)(qg + d0 * 16 + hi * 8 + 4);
; #pragma unroll
;             for (int j = 0; j < 4; ++j) { v[d0][j] *= rs * c * g0[j]; v[d0][4 + j] *= rs * c * g1[j]; } }
;         if (QPRE == 3) {
;             const int pos = q0 + wid * 32 + l32;
; #pragma unroll
;             for (int j = 0; j < 8; ++j) { float cs, sn; rope_cs(pos, 2 * (8 * hi + j), cs, sn); const float x1 = v[ND0 - 2][j], x2 = v[ND0 - 1][j];
;     ...
;     for (int j = 0; j < NKL; ++j) { const int ci = tid + 512 * j; const int row = ci / KCH, cc = ci % KCH; kof[j] = (unsigned)(row * ldk + cc * 8); }
; #pragma unroll
;     for (int j = 0; j < NVL; ++j) { const int ci = tid + 512 * j; const int d = ci >> 3, cc = ci & 7; vof[j] = (unsigned)(d * ldvt + cc * 8); }
	v_mul_f64 v[78:79], v[208:209], v[80:81]
	v_rndne_f64_e32 v[78:79], v[78:79]
	v_fma_f64 v[76:77], v[208:209], v[80:81], -v[78:79]
	v_cvt_f32_f64_e32 v76, v[76:77]
	v_cos_f32_e32 v78, v76
	v_sin_f32_e32 v76, v76
	s_waitcnt vmcnt(0)
	v_mul_f64 v[86:87], v[210:211], v[80:81]
	v_rndne_f64_e32 v[86:87], v[86:87]
	v_fma_f64 v[84:85], v[210:211], v[80:81], -v[86:87]
	v_cvt_f32_f64_e32 v77, v[84:85]
	v_cos_f32_e32 v79, v77
	v_sin_f32_e32 v77, v77
	v_lshl_add_u64 v[84:85], s[4:5], 0, v[82:83]
	s_getpc_b64 s[4:5]
	s_add_u32 s4, s4, _ZL8ROPE_REV@rel32@lo+84
	s_addc_u32 s5, s5, _ZL8ROPE_REV@rel32@hi+92
	s_waitcnt vmcnt(0)
	v_mul_f64 v[86:87], v[212:213], v[80:81]
	v_rndne_f64_e32 v[86:87], v[86:87]
	v_fma_f64 v[84:85], v[212:213], v[80:81], -v[86:87]
	v_cvt_f32_f64_e32 v84, v[84:85]
	v_cos_f32_e32 v130, v84
	v_sin_f32_e32 v128, v84
	v_lshl_add_u64 v[84:85], s[4:5], 0, v[82:83]
	s_getpc_b64 s[4:5]
	s_add_u32 s4, s4, _ZL8ROPE_REV@rel32@lo+100
	s_addc_u32 s5, s5, _ZL8ROPE_REV@rel32@hi+108
	s_waitcnt vmcnt(0)
	v_mul_f64 v[86:87], v[214:215], v[80:81]
	v_rndne_f64_e32 v[86:87], v[86:87]
	v_fma_f64 v[84:85], v[214:215], v[80:81], -v[86:87]
	v_cvt_f32_f64_e32 v84, v[84:85]
	v_cos_f32_e32 v131, v84
	v_sin_f32_e32 v129, v84
	v_lshl_add_u64 v[84:85], s[4:5], 0, v[82:83]
	s_getpc_b64 s[4:5]
	s_add_u32 s4, s4, _ZL8ROPE_REV@rel32@lo+116
	s_addc_u32 s5, s5, _ZL8ROPE_REV@rel32@hi+124
	v_lshl_add_u64 v[82:83], s[4:5], 0, v[82:83]
	v_mul_hi_i32 v86, v172, s40
	v_lshrrev_b32_e32 v87, 31, v86
	v_ashrrev_i32_e32 v86, 1, v86
	v_add_u32_e32 v171, v86, v87
	v_mul_lo_u32 v86, v171, 12
	v_mul_lo_u32 v87, v171, s41
	v_sub_u32_e32 v174, v172, v86
	v_mul_f32_e32 v86, v161, v161
	v_lshl_add_u32 v152, v174, 3, v87
	s_waitcnt vmcnt(0)
	v_mul_f64 v[54:55], v[216:217], v[80:81]
	v_rndne_f64_e32 v[54:55], v[54:55]
	v_fma_f64 v[54:55], v[216:217], v[80:81], -v[54:55]
	v_cvt_f32_f64_e32 v54, v[54:55]
	v_cos_f32_e32 v56, v54
	v_sin_f32_e32 v54, v54
	v_mul_f32_e32 v84, v51, v51
	v_pk_add_f32 v[48:49], v[84:85], v[48:49] op_sel_hi:[0,1]
	v_pk_fma_f32 v[48:49], v[160:161], v[160:161], v[48:49]
	s_nop 0
	v_pk_add_f32 v[48:49], v[86:87], v[48:49] op_sel_hi:[0,1]
	v_pk_fma_f32 v[48:49], v[158:159], v[158:159], v[48:49]
	s_nop 0
	v_pk_add_f32 v[48:49], v[88:89], v[48:49] op_sel_hi:[0,1]
	v_pk_fma_f32 v[48:49], v[52:53], v[52:53], v[48:49]
	s_nop 0
	v_pk_add_f32 v[48:49], v[90:91], v[48:49] op_sel_hi:[0,1]
	v_pk_fma_f32 v[48:49], v[154:155], v[154:155], v[48:49]
	s_nop 0
	v_pk_add_f32 v[48:49], v[92:93], v[48:49] op_sel_hi:[0,1]
	v_pk_fma_f32 v[48:49], v[156:157], v[156:157], v[48:49]
	s_nop 0
	v_pk_add_f32 v[48:49], v[94:95], v[48:49] op_sel_hi:[0,1]
	v_pk_fma_f32 v[48:49], v[150:151], v[150:151], v[48:49]
	s_nop 0
	v_pk_add_f32 v[48:49], v[96:97], v[48:49] op_sel_hi:[0,1]
	v_pk_fma_f32 v[48:49], v[148:149], v[148:149], v[48:49]
	s_nop 0
	v_pk_add_f32 v[48:49], v[98:99], v[48:49] op_sel_hi:[0,1]
	v_pk_fma_f32 v[48:49], v[58:59], v[58:59], v[48:49]
	s_nop 0
	v_pk_add_f32 v[48:49], v[100:101], v[48:49] op_sel_hi:[0,1]
	v_pk_fma_f32 v[48:49], v[146:147], v[146:147], v[48:49]
	s_nop 0
	v_pk_add_f32 v[48:49], v[102:103], v[48:49] op_sel_hi:[0,1]
	v_pk_fma_f32 v[48:49], v[144:145], v[144:145], v[48:49]
	s_nop 0
	v_pk_add_f32 v[48:49], v[104:105], v[48:49] op_sel_hi:[0,1]
	v_pk_fma_f32 v[48:49], v[60:61], v[60:61], v[48:49]
	s_nop 0
	v_pk_add_f32 v[48:49], v[106:107], v[48:49] op_sel_hi:[0,1]
	v_pk_fma_f32 v[48:49], v[62:63], v[62:63], v[48:49]
	s_nop 0
	v_pk_add_f32 v[48:49], v[108:109], v[48:49] op_sel_hi:[0,1]
	v_pk_fma_f32 v[48:49], v[142:143], v[142:143], v[48:49]
	s_nop 0
	v_pk_add_f32 v[48:49], v[110:111], v[48:49] op_sel_hi:[0,1]
	v_pk_fma_f32 v[48:49], v[140:141], v[140:141], v[48:49]
	s_nop 0
	v_pk_add_f32 v[48:49], v[112:113], v[48:49] op_sel_hi:[0,1]
	v_pk_fma_f32 v[48:49], v[68:69], v[68:69], v[48:49]
	s_nop 0
	v_pk_add_f32 v[48:49], v[114:115], v[48:49] op_sel_hi:[0,1]
	v_pk_fma_f32 v[48:49], v[138:139], v[138:139], v[48:49]
	s_nop 0
	v_pk_add_f32 v[48:49], v[116:117], v[48:49] op_sel_hi:[0,1]
	v_pk_fma_f32 v[48:49], v[136:137], v[136:137], v[48:49]
	s_nop 0
	v_pk_add_f32 v[48:49], v[118:119], v[48:49] op_sel_hi:[0,1]
	v_pk_fma_f32 v[48:49], v[134:135], v[134:135], v[48:49]
	s_nop 0
	v_pk_add_f32 v[48:49], v[120:121], v[48:49] op_sel_hi:[0,1]
	v_pk_fma_f32 v[48:49], v[64:65], v[64:65], v[48:49]
	s_nop 0
	v_pk_add_f32 v[48:49], v[122:123], v[48:49] op_sel_hi:[0,1]
	v_pk_fma_f32 v[48:49], v[70:71], v[70:71], v[48:49]
	s_nop 0
	v_pk_add_f32 v[48:49], v[124:125], v[48:49] op_sel_hi:[0,1]
	v_pk_fma_f32 v[48:49], v[66:67], v[66:67], v[48:49]
	s_nop 0
	v_pk_add_f32 v[48:49], v[126:127], v[48:49] op_sel_hi:[0,1]
	v_pk_fma_f32 v[48:49], v[132:133], v[132:133], v[48:49]
	s_nop 0
	v_pk_add_f32 v[164:165], v[164:165], v[48:49] op_sel_hi:[0,1]
	v_mov_b32_e32 v177, v164
	s_nop 1
	v_permlane32_swap_b32_e32 v164, v177
	s_waitcnt vmcnt(0)
	v_mul_f64 v[48:49], v[218:219], v[80:81]
	v_rndne_f64_e32 v[48:49], v[48:49]
	v_fma_f64 v[48:49], v[218:219], v[80:81], -v[48:49]
	v_cvt_f32_f64_e32 v48, v[48:49]
	v_cos_f32_e32 v57, v48
	v_sin_f32_e32 v55, v48
	s_and_saveexec_b64 s[8:9], s[6:7]
	s_cbranch_execz .LBB0_1639
	v_mov_b32_e32 v153, v169
	v_lshl_add_u64 v[48:49], v[152:153], 1, s[10:11]
	global_load_dwordx4 v[80:83], v[48:49], off
